# K-loop heads aligned to 64 bytes (code placement) on top of the ssq-prefetch epilogues
# speedup vs baseline: 1.0038x; 1.0038x over previous
; template <class Epi, class Sched>
; __device__ __forceinline__ void gemm_phase(LAS unsigned char* lds, const Gemm g, const Sched& S, const Epi& E) {
;     ...
;         const bool has_next = S.next(ui + 1, nxt);
;         const char* nA = has_next ? (const char*)g.A + (size_t)nxt.pm * tstepA + (size_t)nxt.kt0 * kstep : cA;
;         const char* nB = has_next ? (const char*)g.Bt + (size_t)nxt.pn * tstepB + (size_t)nxt.kt0 * kstep : cB;
;         const int nt = cur.nkt;
;         if (cur.pm != 32) {
;         for (int t = 0; t < nt; t += 2) {
;     ...
; #pragma unroll
;         for (int a = 0; a < 2; ++a)
; #pragma unroll
;             for (int b = 0; b < 2; ++b)
; #pragma unroll
;                 for (int m = 0; m < 4; ++m)
; #pragma unroll
;                     for (int n = 0; n < 2; ++n) acc[a][b][m][n] = (f32x4){0.f, 0.f, 0.f, 0.f};
.LBB0_166:
	s_ashr_i32 s15, s14, 31
	s_lshl_b64 s[30:31], s[14:15], 20
	v_readlane_b32 s36, v254, 38
	v_readlane_b32 s37, v254, 39
	s_add_u32 s13, s36, s30
	s_addc_u32 s15, s37, s31
	s_ashr_i32 s11, s10, 31
	s_lshl_b64 s[36:37], s[10:11], 7
	s_add_u32 s30, s13, s36
	s_addc_u32 s31, s15, s37
	s_and_b64 s[38:39], s[16:17], exec
	s_cselect_b32 s11, s31, s45
	s_cselect_b32 s15, s30, s44
	s_ashr_i32 s13, s12, 31
	s_lshl_b64 s[38:39], s[12:13], 20
	s_add_u32 s13, s28, s38
	s_addc_u32 s38, s29, s39
	s_add_u32 s36, s13, s36
	s_addc_u32 s37, s38, s37
	s_and_b64 s[38:39], s[16:17], exec
	s_cselect_b32 s13, s37, s53
	s_cselect_b32 s74, s36, s52
	s_add_u32 s75, s52, 0x100
	s_addc_u32 s76, s53, 0
	s_add_u32 s77, s44, 0x100
	s_addc_u32 s78, s45, 0
	s_cmp_eq_u32 s6, 32
	s_mov_b64 s[54:55], -1
	s_cbranch_scc1 .LBB0_175
	s_add_u32 s38, s44, 0x100
	s_addc_u32 s39, s45, 0
	s_add_u32 s40, s52, 0x100
	v_mov_b32_e32 v10, 0
	s_addc_u32 s41, s53, 0
	s_mov_b32 s42, -2
	v_mov_b32_e32 v11, v10
	v_mov_b32_e32 v12, v10
	v_mov_b32_e32 v13, v10
	v_mov_b32_e32 v14, v10
	v_mov_b32_e32 v15, v10
	v_mov_b32_e32 v16, v10
	v_mov_b32_e32 v17, v10
	v_mov_b32_e32 v42, v10
	v_mov_b32_e32 v43, v10
	v_mov_b32_e32 v44, v10
	v_mov_b32_e32 v45, v10
	v_mov_b32_e32 v46, v10
	v_mov_b32_e32 v47, v10
	v_mov_b32_e32 v48, v10
	v_mov_b32_e32 v49, v10
	v_mov_b32_e32 v70, v10
	v_mov_b32_e32 v71, v10
	v_mov_b32_e32 v72, v10
	v_mov_b32_e32 v73, v10
	v_mov_b32_e32 v74, v10
	v_mov_b32_e32 v75, v10
	v_mov_b32_e32 v76, v10
	v_mov_b32_e32 v77, v10
	v_mov_b32_e32 v98, v10
	v_mov_b32_e32 v99, v10
	v_mov_b32_e32 v100, v10
	v_mov_b32_e32 v101, v10
	v_mov_b32_e32 v102, v10
	v_mov_b32_e32 v103, v10
	v_mov_b32_e32 v104, v10
	v_mov_b32_e32 v105, v10
	v_mov_b32_e32 v2, v10
	v_mov_b32_e32 v3, v10
	v_mov_b32_e32 v4, v10
	v_mov_b32_e32 v5, v10
	v_mov_b32_e32 v6, v10
	v_mov_b32_e32 v7, v10
	v_mov_b32_e32 v8, v10
	v_mov_b32_e32 v9, v10
	v_mov_b32_e32 v30, v10
	v_mov_b32_e32 v31, v10
	v_mov_b32_e32 v32, v10
	v_mov_b32_e32 v33, v10
	v_mov_b32_e32 v34, v10
	v_mov_b32_e32 v35, v10
	v_mov_b32_e32 v36, v10
	v_mov_b32_e32 v37, v10
	v_mov_b32_e32 v58, v10
	v_mov_b32_e32 v59, v10
	v_mov_b32_e32 v60, v10
	v_mov_b32_e32 v61, v10
	v_mov_b32_e32 v62, v10
	v_mov_b32_e32 v63, v10
	v_mov_b32_e32 v64, v10
	v_mov_b32_e32 v65, v10
	v_mov_b32_e32 v82, v10
	v_mov_b32_e32 v83, v10
	v_mov_b32_e32 v84, v10
	v_mov_b32_e32 v85, v10
	v_mov_b32_e32 v86, v10
	v_mov_b32_e32 v87, v10
	v_mov_b32_e32 v88, v10
	v_mov_b32_e32 v89, v10
	v_mov_b32_e32 v18, v10
	v_mov_b32_e32 v19, v10
	v_mov_b32_e32 v20, v10
	v_mov_b32_e32 v21, v10
	v_mov_b32_e32 v22, v10
	v_mov_b32_e32 v23, v10
	v_mov_b32_e32 v24, v10
	v_mov_b32_e32 v25, v10
	v_mov_b32_e32 v50, v10
	v_mov_b32_e32 v51, v10
	v_mov_b32_e32 v52, v10
	v_mov_b32_e32 v53, v10
	v_mov_b32_e32 v54, v10
	v_mov_b32_e32 v55, v10
	v_mov_b32_e32 v56, v10
	v_mov_b32_e32 v57, v10
	v_mov_b32_e32 v90, v10
	v_mov_b32_e32 v91, v10
	v_mov_b32_e32 v92, v10
	v_mov_b32_e32 v93, v10
	v_mov_b32_e32 v94, v10
	v_mov_b32_e32 v95, v10
	v_mov_b32_e32 v96, v10
	v_mov_b32_e32 v97, v10
	v_mov_b32_e32 v118, v10
	v_mov_b32_e32 v119, v10
	v_mov_b32_e32 v120, v10
	v_mov_b32_e32 v121, v10
	v_mov_b32_e32 v126, v10
	v_mov_b32_e32 v127, v10
	v_mov_b32_e32 v128, v10
	v_mov_b32_e32 v129, v10
	v_mov_b32_e32 v26, v10
	v_mov_b32_e32 v27, v10
	v_mov_b32_e32 v28, v10
	v_mov_b32_e32 v29, v10
	v_mov_b32_e32 v38, v10
	v_mov_b32_e32 v39, v10
	v_mov_b32_e32 v40, v10
	v_mov_b32_e32 v41, v10
	v_mov_b32_e32 v66, v10
	v_mov_b32_e32 v67, v10
	v_mov_b32_e32 v68, v10
	v_mov_b32_e32 v69, v10
	v_mov_b32_e32 v78, v10
	v_mov_b32_e32 v79, v10
	v_mov_b32_e32 v80, v10
	v_mov_b32_e32 v81, v10
	v_mov_b32_e32 v106, v10
	v_mov_b32_e32 v107, v10
	v_mov_b32_e32 v108, v10
	v_mov_b32_e32 v109, v10
	v_mov_b32_e32 v110, v10
	v_mov_b32_e32 v111, v10
	v_mov_b32_e32 v112, v10
	v_mov_b32_e32 v113, v10
	v_mov_b32_e32 v114, v10
	v_mov_b32_e32 v115, v10
	v_mov_b32_e32 v116, v10
	v_mov_b32_e32 v117, v10
	v_mov_b32_e32 v122, v10
	v_mov_b32_e32 v123, v10
	v_mov_b32_e32 v124, v10
	v_mov_b32_e32 v125, v10
	.p2align	6

; template <class Epi, class Sched>
; __device__ __forceinline__ void gemm_phase(LAS unsigned char* lds, const Gemm g, const Sched& S, const Epi& E) {
;     ...
;         } else {
;         for (int t = 0; t < nt; t += 2) {
;     ...
; #pragma unroll
;         for (int a = 0; a < 2; ++a)
; #pragma unroll
;             for (int b = 0; b < 2; ++b)
; #pragma unroll
;                 for (int m = 0; m < 4; ++m)
; #pragma unroll
;                     for (int n = 0; n < 2; ++n) acc[a][b][m][n] = (f32x4){0.f, 0.f, 0.f, 0.f};
.LBB0_175:
	s_and_b64 vcc, exec, s[54:55]
	s_cbranch_vccz .LBB0_170
	v_mov_b32_e32 v18, 0
	s_mov_b32 s38, -2
	v_mov_b32_e32 v19, v18
	v_mov_b32_e32 v20, v18
	v_mov_b32_e32 v21, v18
	v_mov_b32_e32 v22, v18
	v_mov_b32_e32 v23, v18
	v_mov_b32_e32 v24, v18
	v_mov_b32_e32 v25, v18
	v_mov_b32_e32 v50, v18
	v_mov_b32_e32 v51, v18
	v_mov_b32_e32 v52, v18
	v_mov_b32_e32 v53, v18
	v_mov_b32_e32 v54, v18
	v_mov_b32_e32 v55, v18
	v_mov_b32_e32 v56, v18
	v_mov_b32_e32 v57, v18
	v_mov_b32_e32 v90, v18
	v_mov_b32_e32 v91, v18
	v_mov_b32_e32 v92, v18
	v_mov_b32_e32 v93, v18
	v_mov_b32_e32 v94, v18
	v_mov_b32_e32 v95, v18
	v_mov_b32_e32 v96, v18
	v_mov_b32_e32 v97, v18
	v_mov_b32_e32 v118, v18
	v_mov_b32_e32 v119, v18
	v_mov_b32_e32 v120, v18
	v_mov_b32_e32 v121, v18
	v_mov_b32_e32 v126, v18
	v_mov_b32_e32 v127, v18
	v_mov_b32_e32 v128, v18
	v_mov_b32_e32 v129, v18
	v_mov_b32_e32 v26, v18
	v_mov_b32_e32 v27, v18
	v_mov_b32_e32 v28, v18
	v_mov_b32_e32 v29, v18
	v_mov_b32_e32 v38, v18
	v_mov_b32_e32 v39, v18
	v_mov_b32_e32 v40, v18
	v_mov_b32_e32 v41, v18
	v_mov_b32_e32 v66, v18
	v_mov_b32_e32 v67, v18
	v_mov_b32_e32 v68, v18
	v_mov_b32_e32 v69, v18
	v_mov_b32_e32 v78, v18
	v_mov_b32_e32 v79, v18
	v_mov_b32_e32 v80, v18
	v_mov_b32_e32 v81, v18
	v_mov_b32_e32 v106, v18
	v_mov_b32_e32 v107, v18
	v_mov_b32_e32 v108, v18
	v_mov_b32_e32 v109, v18
	v_mov_b32_e32 v110, v18
	v_mov_b32_e32 v111, v18
	v_mov_b32_e32 v112, v18
	v_mov_b32_e32 v113, v18
	v_mov_b32_e32 v114, v18
	v_mov_b32_e32 v115, v18
	v_mov_b32_e32 v116, v18
	v_mov_b32_e32 v117, v18
	v_mov_b32_e32 v122, v18
	v_mov_b32_e32 v123, v18
	v_mov_b32_e32 v124, v18
	v_mov_b32_e32 v125, v18
	.p2align	6

; template <class Epi, class Sched>
; __device__ __forceinline__ void gemm_phase(LAS unsigned char* lds, const Gemm g, const Sched& S, const Epi& E) {
;     ...
;         const bool has_next = S.next(ui + 1, nxt);
;         const char* nA = has_next ? (const char*)g.A + (size_t)nxt.pm * tstepA + (size_t)nxt.kt0 * kstep : cA;
;         const char* nB = has_next ? (const char*)g.Bt + (size_t)nxt.pn * tstepB + (size_t)nxt.kt0 * kstep : cB;
;         const int nt = cur.nkt;
;         if (cur.pm != 32) {
;         for (int t = 0; t < nt; t += 2) {
;             const bool last = (t == nt - 2);
;     ...
; #pragma unroll
;         for (int a = 0; a < 2; ++a)
; #pragma unroll
;             for (int b = 0; b < 2; ++b)
; #pragma unroll
;                 for (int m = 0; m < 4; ++m)
; #pragma unroll
;                     for (int n = 0; n < 2; ++n) acc[a][b][m][n] = (f32x4){0.f, 0.f, 0.f, 0.f};
.LBB0_245:
	s_cmp_lg_u32 s76, 32
	s_cselect_b64 s[44:45], -1, 0
	s_add_i32 s37, s33, -2
	s_add_u32 s78, s54, 0x100
	s_addc_u32 s79, s55, 0
	s_waitcnt lgkmcnt(0)
	s_add_u32 s80, s52, 0x100
	s_addc_u32 s81, s53, 0
	s_cmp_eq_u32 s76, 32
	s_mov_b64 s[56:57], -1
	s_cbranch_scc1 .LBB0_253
	s_add_u32 s38, s52, 0x100
	s_addc_u32 s39, s53, 0
	s_add_u32 s40, s54, 0x100
	v_mov_b32_e32 v66, 0
	s_addc_u32 s41, s55, 0
	s_mov_b32 s42, 0
	v_mov_b32_e32 v67, v66
	v_mov_b32_e32 v68, v66
	v_mov_b32_e32 v69, v66
	v_mov_b32_e32 v70, v66
	v_mov_b32_e32 v71, v66
	v_mov_b32_e32 v72, v66
	v_mov_b32_e32 v73, v66
	v_mov_b32_e32 v74, v66
	v_mov_b32_e32 v75, v66
	v_mov_b32_e32 v76, v66
	v_mov_b32_e32 v77, v66
	v_mov_b32_e32 v78, v66
	v_mov_b32_e32 v79, v66
	v_mov_b32_e32 v80, v66
	v_mov_b32_e32 v81, v66
	v_mov_b32_e32 v86, v66
	v_mov_b32_e32 v87, v66
	v_mov_b32_e32 v88, v66
	v_mov_b32_e32 v89, v66
	v_mov_b32_e32 v94, v66
	v_mov_b32_e32 v95, v66
	v_mov_b32_e32 v96, v66
	v_mov_b32_e32 v97, v66
	v_mov_b32_e32 v102, v66
	v_mov_b32_e32 v103, v66
	v_mov_b32_e32 v104, v66
	v_mov_b32_e32 v105, v66
	v_mov_b32_e32 v110, v66
	v_mov_b32_e32 v111, v66
	v_mov_b32_e32 v112, v66
	v_mov_b32_e32 v113, v66
	v_mov_b32_e32 v82, v66
	v_mov_b32_e32 v83, v66
	v_mov_b32_e32 v84, v66
	v_mov_b32_e32 v85, v66
	v_mov_b32_e32 v90, v66
	v_mov_b32_e32 v91, v66
	v_mov_b32_e32 v92, v66
	v_mov_b32_e32 v93, v66
	v_mov_b32_e32 v98, v66
	v_mov_b32_e32 v99, v66
	v_mov_b32_e32 v100, v66
	v_mov_b32_e32 v101, v66
	v_mov_b32_e32 v106, v66
	v_mov_b32_e32 v107, v66
	v_mov_b32_e32 v108, v66
	v_mov_b32_e32 v109, v66
	v_mov_b32_e32 v114, v66
	v_mov_b32_e32 v115, v66
	v_mov_b32_e32 v116, v66
	v_mov_b32_e32 v117, v66
	v_mov_b32_e32 v118, v66
	v_mov_b32_e32 v119, v66
	v_mov_b32_e32 v120, v66
	v_mov_b32_e32 v121, v66
	v_mov_b32_e32 v122, v66
	v_mov_b32_e32 v123, v66
	v_mov_b32_e32 v124, v66
	v_mov_b32_e32 v125, v66
	v_mov_b32_e32 v126, v66
	v_mov_b32_e32 v127, v66
	v_mov_b32_e32 v128, v66
	v_mov_b32_e32 v129, v66
	v_mov_b32_e32 v2, v66
	v_mov_b32_e32 v3, v66
	v_mov_b32_e32 v4, v66
	v_mov_b32_e32 v5, v66
	v_mov_b32_e32 v6, v66
	v_mov_b32_e32 v7, v66
	v_mov_b32_e32 v8, v66
	v_mov_b32_e32 v9, v66
	v_mov_b32_e32 v10, v66
	v_mov_b32_e32 v11, v66
	v_mov_b32_e32 v12, v66
	v_mov_b32_e32 v13, v66
	v_mov_b32_e32 v14, v66
	v_mov_b32_e32 v15, v66
	v_mov_b32_e32 v16, v66
	v_mov_b32_e32 v17, v66
	v_mov_b32_e32 v18, v66
	v_mov_b32_e32 v19, v66
	v_mov_b32_e32 v20, v66
	v_mov_b32_e32 v21, v66
	v_mov_b32_e32 v26, v66
	v_mov_b32_e32 v27, v66
	v_mov_b32_e32 v28, v66
	v_mov_b32_e32 v29, v66
	v_mov_b32_e32 v34, v66
	v_mov_b32_e32 v35, v66
	v_mov_b32_e32 v36, v66
	v_mov_b32_e32 v37, v66
	v_mov_b32_e32 v42, v66
	v_mov_b32_e32 v43, v66
	v_mov_b32_e32 v44, v66
	v_mov_b32_e32 v45, v66
	v_mov_b32_e32 v22, v66
	v_mov_b32_e32 v23, v66
	v_mov_b32_e32 v24, v66
	v_mov_b32_e32 v25, v66
	v_mov_b32_e32 v30, v66
	v_mov_b32_e32 v31, v66
	v_mov_b32_e32 v32, v66
	v_mov_b32_e32 v33, v66
	v_mov_b32_e32 v38, v66
	v_mov_b32_e32 v39, v66
	v_mov_b32_e32 v40, v66
	v_mov_b32_e32 v41, v66
	v_mov_b32_e32 v46, v66
	v_mov_b32_e32 v47, v66
	v_mov_b32_e32 v48, v66
	v_mov_b32_e32 v49, v66
	v_mov_b32_e32 v50, v66
	v_mov_b32_e32 v51, v66
	v_mov_b32_e32 v52, v66
	v_mov_b32_e32 v53, v66
	v_mov_b32_e32 v54, v66
	v_mov_b32_e32 v55, v66
	v_mov_b32_e32 v56, v66
	v_mov_b32_e32 v57, v66
	v_mov_b32_e32 v58, v66
	v_mov_b32_e32 v59, v66
	v_mov_b32_e32 v60, v66
	v_mov_b32_e32 v61, v66
	v_mov_b32_e32 v62, v66
	v_mov_b32_e32 v63, v66
	v_mov_b32_e32 v64, v66
	v_mov_b32_e32 v65, v66
	.p2align	6

; template <class Epi, class Sched>
; __device__ __forceinline__ void gemm_phase(LAS unsigned char* lds, const Gemm g, const Sched& S, const Epi& E) {
;     ...
;         } else {
;         for (int t = 0; t < nt; t += 2) {
;     ...
; #pragma unroll
;         for (int a = 0; a < 2; ++a)
; #pragma unroll
;             for (int b = 0; b < 2; ++b)
; #pragma unroll
;                 for (int m = 0; m < 4; ++m)
; #pragma unroll
;                     for (int n = 0; n < 2; ++n) acc[a][b][m][n] = (f32x4){0.f, 0.f, 0.f, 0.f};
.LBB0_253:
	s_and_b64 vcc, exec, s[56:57]
	s_cbranch_vccz .LBB0_249
	v_mov_b32_e32 v2, 0
	s_mov_b32 s39, 0
	v_mov_b32_e32 v3, v2
	v_mov_b32_e32 v4, v2
	v_mov_b32_e32 v5, v2
	v_mov_b32_e32 v6, v2
	v_mov_b32_e32 v7, v2
	v_mov_b32_e32 v8, v2
	v_mov_b32_e32 v9, v2
	v_mov_b32_e32 v10, v2
	v_mov_b32_e32 v11, v2
	v_mov_b32_e32 v12, v2
	v_mov_b32_e32 v13, v2
	v_mov_b32_e32 v14, v2
	v_mov_b32_e32 v15, v2
	v_mov_b32_e32 v16, v2
	v_mov_b32_e32 v17, v2
	v_mov_b32_e32 v18, v2
	v_mov_b32_e32 v19, v2
	v_mov_b32_e32 v20, v2
	v_mov_b32_e32 v21, v2
	v_mov_b32_e32 v26, v2
	v_mov_b32_e32 v27, v2
	v_mov_b32_e32 v28, v2
	v_mov_b32_e32 v29, v2
	v_mov_b32_e32 v34, v2
	v_mov_b32_e32 v35, v2
	v_mov_b32_e32 v36, v2
	v_mov_b32_e32 v37, v2
	v_mov_b32_e32 v42, v2
	v_mov_b32_e32 v43, v2
	v_mov_b32_e32 v44, v2
	v_mov_b32_e32 v45, v2
	v_mov_b32_e32 v22, v2
	v_mov_b32_e32 v23, v2
	v_mov_b32_e32 v24, v2
	v_mov_b32_e32 v25, v2
	v_mov_b32_e32 v30, v2
	v_mov_b32_e32 v31, v2
	v_mov_b32_e32 v32, v2
	v_mov_b32_e32 v33, v2
	v_mov_b32_e32 v38, v2
	v_mov_b32_e32 v39, v2
	v_mov_b32_e32 v40, v2
	v_mov_b32_e32 v41, v2
	v_mov_b32_e32 v46, v2
	v_mov_b32_e32 v47, v2
	v_mov_b32_e32 v48, v2
	v_mov_b32_e32 v49, v2
	v_mov_b32_e32 v50, v2
	v_mov_b32_e32 v51, v2
	v_mov_b32_e32 v52, v2
	v_mov_b32_e32 v53, v2
	v_mov_b32_e32 v54, v2
	v_mov_b32_e32 v55, v2
	v_mov_b32_e32 v56, v2
	v_mov_b32_e32 v57, v2
	v_mov_b32_e32 v58, v2
	v_mov_b32_e32 v59, v2
	v_mov_b32_e32 v60, v2
	v_mov_b32_e32 v61, v2
	v_mov_b32_e32 v62, v2
	v_mov_b32_e32 v63, v2
	v_mov_b32_e32 v64, v2
	v_mov_b32_e32 v65, v2
	.p2align	6

; template <class Epi, class Sched>
; __device__ __forceinline__ void gemm_phase(LAS unsigned char* lds, const Gemm g, const Sched& S, const Epi& E) {
;     ...
;         const bool has_next = S.next(ui + 1, nxt);
;         const char* nA = has_next ? (const char*)g.A + (size_t)nxt.pm * tstepA + (size_t)nxt.kt0 * kstep : cA;
;         const char* nB = has_next ? (const char*)g.Bt + (size_t)nxt.pn * tstepB + (size_t)nxt.kt0 * kstep : cB;
;         const int nt = cur.nkt;
;         if (cur.pm != 32) {
;         for (int t = 0; t < nt; t += 2) {
;     ...
; #pragma unroll
;         for (int a = 0; a < 2; ++a)
; #pragma unroll
;             for (int b = 0; b < 2; ++b)
; #pragma unroll
;                 for (int m = 0; m < 4; ++m)
; #pragma unroll
;                     for (int n = 0; n < 2; ++n) acc[a][b][m][n] = (f32x4){0.f, 0.f, 0.f, 0.f};
.LBB0_333:
	s_ashr_i32 s91, s90, 31
	s_lshl_b64 s[30:31], s[90:91], 20
	v_readlane_b32 s38, v254, 38
	v_readlane_b32 s39, v254, 39
	s_add_u32 s5, s38, s30
	s_addc_u32 s18, s39, s31
	s_ashr_i32 s73, s72, 31
	s_lshl_b64 s[30:31], s[72:73], 7
	s_add_u32 s94, s5, s30
	s_addc_u32 s95, s18, s31
	s_and_b64 s[38:39], s[92:93], exec
	s_cselect_b32 s5, s95, s7
	s_cselect_b32 s73, s94, s6
	s_ashr_i32 s89, s88, 31
	s_lshl_b64 s[38:39], s[88:89], 20
	s_add_u32 s18, s49, s38
	s_addc_u32 s38, s52, s39
	s_add_u32 s96, s18, s30
	s_addc_u32 s97, s38, s31
	s_and_b64 s[30:31], s[92:93], exec
	s_cselect_b32 s89, s97, s9
	s_cselect_b32 s91, s96, s8
	s_cmp_eq_u32 s90, 32
	s_cselect_b64 s[30:31], -1, 0
	s_cmp_eq_u32 s4, 32
	s_mov_b64 s[74:75], -1
	s_cbranch_scc1 .LBB0_349
	v_mov_b32_e32 v2, 0
	s_mov_b32 s38, 0
	v_mov_b32_e32 v3, v2
	v_mov_b32_e32 v4, v2
	v_mov_b32_e32 v5, v2
	v_mov_b32_e32 v6, v2
	v_mov_b32_e32 v7, v2
	v_mov_b32_e32 v8, v2
	v_mov_b32_e32 v9, v2
	v_mov_b32_e32 v18, v2
	v_mov_b32_e32 v19, v2
	v_mov_b32_e32 v20, v2
	v_mov_b32_e32 v21, v2
	v_mov_b32_e32 v22, v2
	v_mov_b32_e32 v23, v2
	v_mov_b32_e32 v24, v2
	v_mov_b32_e32 v25, v2
	v_mov_b32_e32 v34, v2
	v_mov_b32_e32 v35, v2
	v_mov_b32_e32 v36, v2
	v_mov_b32_e32 v37, v2
	v_mov_b32_e32 v38, v2
	v_mov_b32_e32 v39, v2
	v_mov_b32_e32 v40, v2
	v_mov_b32_e32 v41, v2
	v_mov_b32_e32 v58, v2
	v_mov_b32_e32 v59, v2
	v_mov_b32_e32 v60, v2
	v_mov_b32_e32 v61, v2
	v_mov_b32_e32 v62, v2
	v_mov_b32_e32 v63, v2
	v_mov_b32_e32 v64, v2
	v_mov_b32_e32 v65, v2
	v_mov_b32_e32 v10, v2
	v_mov_b32_e32 v11, v2
	v_mov_b32_e32 v12, v2
	v_mov_b32_e32 v13, v2
	v_mov_b32_e32 v14, v2
	v_mov_b32_e32 v15, v2
	v_mov_b32_e32 v16, v2
	v_mov_b32_e32 v17, v2
	v_mov_b32_e32 v26, v2
	v_mov_b32_e32 v27, v2
	v_mov_b32_e32 v28, v2
	v_mov_b32_e32 v29, v2
	v_mov_b32_e32 v30, v2
	v_mov_b32_e32 v31, v2
	v_mov_b32_e32 v32, v2
	v_mov_b32_e32 v33, v2
	v_mov_b32_e32 v42, v2
	v_mov_b32_e32 v43, v2
	v_mov_b32_e32 v44, v2
	v_mov_b32_e32 v45, v2
	v_mov_b32_e32 v46, v2
	v_mov_b32_e32 v47, v2
	v_mov_b32_e32 v48, v2
	v_mov_b32_e32 v49, v2
	v_mov_b32_e32 v74, v2
	v_mov_b32_e32 v75, v2
	v_mov_b32_e32 v76, v2
	v_mov_b32_e32 v77, v2
	v_mov_b32_e32 v78, v2
	v_mov_b32_e32 v79, v2
	v_mov_b32_e32 v80, v2
	v_mov_b32_e32 v81, v2
	v_mov_b32_e32 v50, v2
	v_mov_b32_e32 v51, v2
	v_mov_b32_e32 v52, v2
	v_mov_b32_e32 v53, v2
	v_mov_b32_e32 v54, v2
	v_mov_b32_e32 v55, v2
	v_mov_b32_e32 v56, v2
	v_mov_b32_e32 v57, v2
	v_mov_b32_e32 v82, v2
	v_mov_b32_e32 v83, v2
	v_mov_b32_e32 v84, v2
	v_mov_b32_e32 v85, v2
	v_mov_b32_e32 v86, v2
	v_mov_b32_e32 v87, v2
	v_mov_b32_e32 v88, v2
	v_mov_b32_e32 v89, v2
	v_mov_b32_e32 v98, v2
	v_mov_b32_e32 v99, v2
	v_mov_b32_e32 v100, v2
	v_mov_b32_e32 v101, v2
	v_mov_b32_e32 v102, v2
	v_mov_b32_e32 v103, v2
	v_mov_b32_e32 v104, v2
	v_mov_b32_e32 v105, v2
	v_mov_b32_e32 v114, v2
	v_mov_b32_e32 v115, v2
	v_mov_b32_e32 v116, v2
	v_mov_b32_e32 v117, v2
	v_mov_b32_e32 v118, v2
	v_mov_b32_e32 v119, v2
	v_mov_b32_e32 v120, v2
	v_mov_b32_e32 v121, v2
	v_mov_b32_e32 v66, v2
	v_mov_b32_e32 v67, v2
	v_mov_b32_e32 v68, v2
	v_mov_b32_e32 v69, v2
	v_mov_b32_e32 v70, v2
	v_mov_b32_e32 v71, v2
	v_mov_b32_e32 v72, v2
	v_mov_b32_e32 v73, v2
	v_mov_b32_e32 v90, v2
	v_mov_b32_e32 v91, v2
	v_mov_b32_e32 v92, v2
	v_mov_b32_e32 v93, v2
	v_mov_b32_e32 v94, v2
	v_mov_b32_e32 v95, v2
	v_mov_b32_e32 v96, v2
	v_mov_b32_e32 v97, v2
	v_mov_b32_e32 v106, v2
	v_mov_b32_e32 v107, v2
	v_mov_b32_e32 v108, v2
	v_mov_b32_e32 v109, v2
	v_mov_b32_e32 v110, v2
	v_mov_b32_e32 v111, v2
	v_mov_b32_e32 v112, v2
	v_mov_b32_e32 v113, v2
	v_mov_b32_e32 v122, v2
	v_mov_b32_e32 v123, v2
	v_mov_b32_e32 v124, v2
	v_mov_b32_e32 v125, v2
	v_mov_b32_e32 v126, v2
	v_mov_b32_e32 v127, v2
	v_mov_b32_e32 v128, v2
	v_mov_b32_e32 v129, v2
	.p2align	6

;     __device__ __forceinline__ void a_ready(const Unit&) const { wait_cnt(w_ready, w_need); }
;     __device__ __forceinline__ void a_ready(const Unit& u) const {
;         if (ready == nullptr || u.pm != 32) return;
;         if (threadIdx.x < 64) {
;             unsigned polls = 0;
;             while ((unsigned)__builtin_amdgcn_readfirstlane(__hip_atomic_load(ready, __ATOMIC_RELAXED, __HIP_MEMORY_SCOPE_AGENT)) < need) { __builtin_amdgcn_s_sleep(2); if (++polls > (1u << 22)) break; }
;             __builtin_amdgcn_fence(__ATOMIC_ACQUIRE, "agent");
;             asm volatile("s_waitcnt vmcnt(0)" ::: "memory");
;         }
;         asm volatile("" ::: "memory"); __builtin_amdgcn_s_barrier(); asm volatile("" ::: "memory");
;     }
.LBB0_352:
	s_or_b64 exec, exec, s[74:75]
	s_barrier
	.p2align	6

; template <class Epi, class Sched>
; __device__ __forceinline__ void gemm_phase(LAS unsigned char* lds, const Gemm g, const Sched& S, const Epi& E) {
;     ...
;         const bool has_next = S.next(ui + 1, nxt);
;         const char* nA = has_next ? (const char*)g.A + (size_t)nxt.pm * tstepA + (size_t)nxt.kt0 * kstep : cA;
;         const char* nB = has_next ? (const char*)g.Bt + (size_t)nxt.pn * tstepB + (size_t)nxt.kt0 * kstep : cB;
;         const int nt = cur.nkt;
;         if (cur.pm != 32) {
;         for (int t = 0; t < nt; t += 2) {
;     ...
; #pragma unroll
;         for (int a = 0; a < 2; ++a)
; #pragma unroll
;             for (int b = 0; b < 2; ++b)
; #pragma unroll
;                 for (int m = 0; m < 4; ++m)
; #pragma unroll
;                     for (int n = 0; n < 2; ++n) acc[a][b][m][n] = (f32x4){0.f, 0.f, 0.f, 0.f};
.LBB0_780:
	s_ashr_i32 s43, s42, 31
	s_lshl_b64 s[36:37], s[42:43], 19
	s_add_u32 s5, s14, s36
	s_addc_u32 s41, s15, s37
	s_ashr_i32 s39, s38, 31
	s_lshl_b64 s[36:37], s[38:39], 7
	s_add_u32 s68, s5, s36
	s_addc_u32 s69, s41, s37
	s_and_b64 s[46:47], s[44:45], exec
	s_cselect_b32 s5, s69, s73
	s_cselect_b32 s39, s68, s72
	s_ashr_i32 s41, s40, 31
	s_lshl_b64 s[46:47], s[40:41], 19
	s_add_u32 s41, s12, s46
	s_addc_u32 s43, s13, s47
	s_add_u32 s70, s41, s36
	s_addc_u32 s71, s43, s37
	s_and_b64 s[36:37], s[44:45], exec
	s_cselect_b32 s41, s71, s75
	s_cselect_b32 s43, s70, s74
	s_add_u32 s89, s74, 0x100
	s_addc_u32 s90, s75, 0
	s_add_u32 s91, s72, 0x100
	s_addc_u32 s92, s73, 0
	s_cmp_eq_u32 s30, 32
	s_mov_b64 s[36:37], -1
	s_cbranch_scc1 .LBB0_805
	s_add_u32 s46, s72, 0x100
	s_addc_u32 s47, s73, 0
	s_add_u32 s48, s74, 0x100
	v_mov_b32_e32 v2, 0
	s_addc_u32 s49, s75, 0
	s_mov_b32 s50, -2
	s_waitcnt lgkmcnt(0)
	v_mov_b32_e32 v3, v2
	v_mov_b32_e32 v4, v2
	v_mov_b32_e32 v5, v2
	v_mov_b32_e32 v6, v2
	v_mov_b32_e32 v7, v2
	v_mov_b32_e32 v8, v2
	v_mov_b32_e32 v9, v2
	v_mov_b32_e32 v18, v2
	v_mov_b32_e32 v19, v2
	v_mov_b32_e32 v20, v2
	v_mov_b32_e32 v21, v2
	v_mov_b32_e32 v22, v2
	v_mov_b32_e32 v23, v2
	v_mov_b32_e32 v24, v2
	v_mov_b32_e32 v25, v2
	v_mov_b32_e32 v34, v2
	v_mov_b32_e32 v35, v2
	v_mov_b32_e32 v36, v2
	v_mov_b32_e32 v37, v2
	v_mov_b32_e32 v38, v2
	v_mov_b32_e32 v39, v2
	v_mov_b32_e32 v40, v2
	v_mov_b32_e32 v41, v2
	v_mov_b32_e32 v66, v2
	v_mov_b32_e32 v67, v2
	v_mov_b32_e32 v68, v2
	v_mov_b32_e32 v69, v2
	v_mov_b32_e32 v70, v2
	v_mov_b32_e32 v71, v2
	v_mov_b32_e32 v72, v2
	v_mov_b32_e32 v73, v2
	v_mov_b32_e32 v10, v2
	v_mov_b32_e32 v11, v2
	v_mov_b32_e32 v12, v2
	v_mov_b32_e32 v13, v2
	v_mov_b32_e32 v14, v2
	v_mov_b32_e32 v15, v2
	v_mov_b32_e32 v16, v2
	v_mov_b32_e32 v17, v2
	v_mov_b32_e32 v26, v2
	v_mov_b32_e32 v27, v2
	v_mov_b32_e32 v28, v2
	v_mov_b32_e32 v29, v2
	v_mov_b32_e32 v30, v2
	v_mov_b32_e32 v31, v2
	v_mov_b32_e32 v32, v2
	v_mov_b32_e32 v33, v2
	v_mov_b32_e32 v50, v2
	v_mov_b32_e32 v51, v2
	v_mov_b32_e32 v52, v2
	v_mov_b32_e32 v53, v2
	v_mov_b32_e32 v54, v2
	v_mov_b32_e32 v55, v2
	v_mov_b32_e32 v56, v2
	v_mov_b32_e32 v57, v2
	v_mov_b32_e32 v82, v2
	v_mov_b32_e32 v83, v2
	v_mov_b32_e32 v84, v2
	v_mov_b32_e32 v85, v2
	v_mov_b32_e32 v86, v2
	v_mov_b32_e32 v87, v2
	v_mov_b32_e32 v88, v2
	v_mov_b32_e32 v89, v2
	v_mov_b32_e32 v42, v2
	v_mov_b32_e32 v43, v2
	v_mov_b32_e32 v44, v2
	v_mov_b32_e32 v45, v2
	v_mov_b32_e32 v46, v2
	v_mov_b32_e32 v47, v2
	v_mov_b32_e32 v48, v2
	v_mov_b32_e32 v49, v2
	v_mov_b32_e32 v74, v2
	v_mov_b32_e32 v75, v2
	v_mov_b32_e32 v76, v2
	v_mov_b32_e32 v77, v2
	v_mov_b32_e32 v78, v2
	v_mov_b32_e32 v79, v2
	v_mov_b32_e32 v80, v2
	v_mov_b32_e32 v81, v2
	v_mov_b32_e32 v98, v2
	v_mov_b32_e32 v99, v2
	v_mov_b32_e32 v100, v2
	v_mov_b32_e32 v101, v2
	v_mov_b32_e32 v102, v2
	v_mov_b32_e32 v103, v2
	v_mov_b32_e32 v104, v2
	v_mov_b32_e32 v105, v2
	v_mov_b32_e32 v114, v2
	v_mov_b32_e32 v115, v2
	v_mov_b32_e32 v116, v2
	v_mov_b32_e32 v117, v2
	v_mov_b32_e32 v118, v2
	v_mov_b32_e32 v119, v2
	v_mov_b32_e32 v120, v2
	v_mov_b32_e32 v121, v2
	v_mov_b32_e32 v58, v2
	v_mov_b32_e32 v59, v2
	v_mov_b32_e32 v60, v2
	v_mov_b32_e32 v61, v2
	v_mov_b32_e32 v62, v2
	v_mov_b32_e32 v63, v2
	v_mov_b32_e32 v64, v2
	v_mov_b32_e32 v65, v2
	v_mov_b32_e32 v90, v2
	v_mov_b32_e32 v91, v2
	v_mov_b32_e32 v92, v2
	v_mov_b32_e32 v93, v2
	v_mov_b32_e32 v94, v2
	v_mov_b32_e32 v95, v2
	v_mov_b32_e32 v96, v2
	v_mov_b32_e32 v97, v2
	v_mov_b32_e32 v106, v2
	v_mov_b32_e32 v107, v2
	v_mov_b32_e32 v108, v2
	v_mov_b32_e32 v109, v2
	v_mov_b32_e32 v110, v2
	v_mov_b32_e32 v111, v2
	v_mov_b32_e32 v112, v2
	v_mov_b32_e32 v113, v2
	v_mov_b32_e32 v138, v2
	v_mov_b32_e32 v139, v2
	v_mov_b32_e32 v140, v2
	v_mov_b32_e32 v141, v2
	v_mov_b32_e32 v142, v2
	v_mov_b32_e32 v143, v2
	v_mov_b32_e32 v144, v2
	v_mov_b32_e32 v145, v2
	.p2align	6

; template <class Epi, class Sched>
; __device__ __forceinline__ void gemm_phase(LAS unsigned char* lds, const Gemm g, const Sched& S, const Epi& E) {
;     ...
;         } else {
;         for (int t = 0; t < nt; t += 2) {
;     ...
; #pragma unroll
;         for (int a = 0; a < 2; ++a)
; #pragma unroll
;             for (int b = 0; b < 2; ++b)
; #pragma unroll
;                 for (int m = 0; m < 4; ++m)
; #pragma unroll
;                     for (int n = 0; n < 2; ++n) acc[a][b][m][n] = (f32x4){0.f, 0.f, 0.f, 0.f};
.LBB0_805:
	s_and_b64 vcc, exec, s[36:37]
	s_cbranch_vccz .LBB0_784
	v_mov_b32_e32 v42, 0
	s_mov_b32 s46, -2
	v_mov_b32_e32 v43, v42
	v_mov_b32_e32 v44, v42
	v_mov_b32_e32 v45, v42
	v_mov_b32_e32 v46, v42
	v_mov_b32_e32 v47, v42
	v_mov_b32_e32 v48, v42
	v_mov_b32_e32 v49, v42
	v_mov_b32_e32 v74, v42
	v_mov_b32_e32 v75, v42
	v_mov_b32_e32 v76, v42
	v_mov_b32_e32 v77, v42
	v_mov_b32_e32 v78, v42
	v_mov_b32_e32 v79, v42
	v_mov_b32_e32 v80, v42
	v_mov_b32_e32 v81, v42
	v_mov_b32_e32 v98, v42
	v_mov_b32_e32 v99, v42
	v_mov_b32_e32 v100, v42
	v_mov_b32_e32 v101, v42
	v_mov_b32_e32 v102, v42
	v_mov_b32_e32 v103, v42
	v_mov_b32_e32 v104, v42
	v_mov_b32_e32 v105, v42
	v_mov_b32_e32 v114, v42
	v_mov_b32_e32 v115, v42
	v_mov_b32_e32 v116, v42
	v_mov_b32_e32 v117, v42
	v_mov_b32_e32 v118, v42
	v_mov_b32_e32 v119, v42
	v_mov_b32_e32 v120, v42
	v_mov_b32_e32 v121, v42
	v_mov_b32_e32 v58, v42
	v_mov_b32_e32 v59, v42
	v_mov_b32_e32 v60, v42
	v_mov_b32_e32 v61, v42
	v_mov_b32_e32 v62, v42
	v_mov_b32_e32 v63, v42
	v_mov_b32_e32 v64, v42
	v_mov_b32_e32 v65, v42
	v_mov_b32_e32 v90, v42
	v_mov_b32_e32 v91, v42
	v_mov_b32_e32 v92, v42
	v_mov_b32_e32 v93, v42
	v_mov_b32_e32 v94, v42
	v_mov_b32_e32 v95, v42
	v_mov_b32_e32 v96, v42
	v_mov_b32_e32 v97, v42
	v_mov_b32_e32 v106, v42
	v_mov_b32_e32 v107, v42
	v_mov_b32_e32 v108, v42
	v_mov_b32_e32 v109, v42
	v_mov_b32_e32 v110, v42
	v_mov_b32_e32 v111, v42
	v_mov_b32_e32 v112, v42
	v_mov_b32_e32 v113, v42
	v_mov_b32_e32 v138, v42
	v_mov_b32_e32 v139, v42
	v_mov_b32_e32 v140, v42
	v_mov_b32_e32 v141, v42
	v_mov_b32_e32 v142, v42
	v_mov_b32_e32 v143, v42
	v_mov_b32_e32 v144, v42
	v_mov_b32_e32 v145, v42
	.p2align	6

; template <class Epi, class Sched>
; __device__ __forceinline__ void gemm_phase(LAS unsigned char* lds, const Gemm g, const Sched& S, const Epi& E) {
;     ...
;         const bool has_next = S.next(ui + 1, nxt);
;         const char* nA = has_next ? (const char*)g.A + (size_t)nxt.pm * tstepA + (size_t)nxt.kt0 * kstep : cA;
;         const char* nB = has_next ? (const char*)g.Bt + (size_t)nxt.pn * tstepB + (size_t)nxt.kt0 * kstep : cB;
;         const int nt = cur.nkt;
;         if (cur.pm != 32) {
;         for (int t = 0; t < nt; t += 2) {
;     ...
; #pragma unroll
;         for (int a = 0; a < 2; ++a)
; #pragma unroll
;             for (int b = 0; b < 2; ++b)
; #pragma unroll
;                 for (int m = 0; m < 4; ++m)
; #pragma unroll
;                     for (int n = 0; n < 2; ++n) acc[a][b][m][n] = (f32x4){0.f, 0.f, 0.f, 0.f};
.LBB0_996:
	s_ashr_i32 s21, s20, 31
	s_lshl_b64 s[24:25], s[20:21], 20
	s_add_u32 s4, s86, s24
	s_addc_u32 s15, s87, s25
	s_ashr_i32 s13, s12, 31
	s_lshl_b64 s[26:27], s[12:13], 7
	s_add_u32 s24, s4, s26
	s_addc_u32 s25, s15, s27
	s_and_b64 s[38:39], s[22:23], exec
	s_cselect_b32 s13, s25, s31
	s_cselect_b32 s21, s24, s30
	s_ashr_i32 s15, s14, 31
	s_lshl_b64 s[38:39], s[14:15], 20
	s_add_u32 s4, s28, s38
	s_addc_u32 s15, s29, s39
	s_add_u32 s26, s4, s26
	s_addc_u32 s27, s15, s27
	s_and_b64 s[38:39], s[22:23], exec
	s_cselect_b32 s15, s27, s37
	s_cselect_b32 s64, s26, s36
	s_cmp_eq_u32 s20, 32
	s_cselect_b64 s[38:39], -1, 0
	s_cmp_eq_u32 s6, 32
	s_mov_b64 s[40:41], -1
	s_cbranch_scc1 .LBB0_1012
	v_mov_b32_e32 v26, 0
	s_mov_b32 s65, 0
	v_mov_b32_e32 v27, v26
	v_mov_b32_e32 v28, v26
	v_mov_b32_e32 v29, v26
	v_mov_b32_e32 v30, v26
	v_mov_b32_e32 v31, v26
	v_mov_b32_e32 v32, v26
	v_mov_b32_e32 v33, v26
	v_mov_b32_e32 v58, v26
	v_mov_b32_e32 v59, v26
	v_mov_b32_e32 v60, v26
	v_mov_b32_e32 v61, v26
	v_mov_b32_e32 v62, v26
	v_mov_b32_e32 v63, v26
	v_mov_b32_e32 v64, v26
	v_mov_b32_e32 v65, v26
	v_mov_b32_e32 v82, v26
	v_mov_b32_e32 v83, v26
	v_mov_b32_e32 v84, v26
	v_mov_b32_e32 v85, v26
	v_mov_b32_e32 v90, v26
	v_mov_b32_e32 v91, v26
	v_mov_b32_e32 v92, v26
	v_mov_b32_e32 v93, v26
	v_mov_b32_e32 v106, v26
	v_mov_b32_e32 v107, v26
	v_mov_b32_e32 v108, v26
	v_mov_b32_e32 v109, v26
	v_mov_b32_e32 v110, v26
	v_mov_b32_e32 v111, v26
	v_mov_b32_e32 v112, v26
	v_mov_b32_e32 v113, v26
	v_mov_b32_e32 v18, v26
	v_mov_b32_e32 v19, v26
	v_mov_b32_e32 v20, v26
	v_mov_b32_e32 v21, v26
	v_mov_b32_e32 v22, v26
	v_mov_b32_e32 v23, v26
	v_mov_b32_e32 v24, v26
	v_mov_b32_e32 v25, v26
	v_mov_b32_e32 v42, v26
	v_mov_b32_e32 v43, v26
	v_mov_b32_e32 v44, v26
	v_mov_b32_e32 v45, v26
	v_mov_b32_e32 v46, v26
	v_mov_b32_e32 v47, v26
	v_mov_b32_e32 v48, v26
	v_mov_b32_e32 v49, v26
	v_mov_b32_e32 v74, v26
	v_mov_b32_e32 v75, v26
	v_mov_b32_e32 v76, v26
	v_mov_b32_e32 v77, v26
	v_mov_b32_e32 v78, v26
	v_mov_b32_e32 v79, v26
	v_mov_b32_e32 v80, v26
	v_mov_b32_e32 v81, v26
	v_mov_b32_e32 v98, v26
	v_mov_b32_e32 v99, v26
	v_mov_b32_e32 v100, v26
	v_mov_b32_e32 v101, v26
	v_mov_b32_e32 v102, v26
	v_mov_b32_e32 v103, v26
	v_mov_b32_e32 v104, v26
	v_mov_b32_e32 v105, v26
	v_mov_b32_e32 v2, v26
	v_mov_b32_e32 v3, v26
	v_mov_b32_e32 v4, v26
	v_mov_b32_e32 v5, v26
	v_mov_b32_e32 v6, v26
	v_mov_b32_e32 v7, v26
	v_mov_b32_e32 v8, v26
	v_mov_b32_e32 v9, v26
	v_mov_b32_e32 v34, v26
	v_mov_b32_e32 v35, v26
	v_mov_b32_e32 v36, v26
	v_mov_b32_e32 v37, v26
	v_mov_b32_e32 v38, v26
	v_mov_b32_e32 v39, v26
	v_mov_b32_e32 v40, v26
	s_waitcnt vmcnt(1)
	v_mov_b32_e32 v41, v26
	v_mov_b32_e32 v66, v26
	v_mov_b32_e32 v67, v26
	v_mov_b32_e32 v68, v26
	v_mov_b32_e32 v69, v26
	s_waitcnt vmcnt(0)
	v_mov_b32_e32 v70, v26
	v_mov_b32_e32 v71, v26
	v_mov_b32_e32 v72, v26
	v_mov_b32_e32 v73, v26
	v_mov_b32_e32 v118, v26
	v_mov_b32_e32 v119, v26
	v_mov_b32_e32 v120, v26
	v_mov_b32_e32 v121, v26
	v_mov_b32_e32 v126, v26
	v_mov_b32_e32 v127, v26
	v_mov_b32_e32 v128, v26
	v_mov_b32_e32 v129, v26
	v_mov_b32_e32 v10, v26
	v_mov_b32_e32 v11, v26
	v_mov_b32_e32 v12, v26
	v_mov_b32_e32 v13, v26
	v_mov_b32_e32 v14, v26
	v_mov_b32_e32 v15, v26
	v_mov_b32_e32 v16, v26
	v_mov_b32_e32 v17, v26
	v_mov_b32_e32 v50, v26
	v_mov_b32_e32 v51, v26
	v_mov_b32_e32 v52, v26
	v_mov_b32_e32 v53, v26
	v_mov_b32_e32 v54, v26
	v_mov_b32_e32 v55, v26
	v_mov_b32_e32 v56, v26
	v_mov_b32_e32 v57, v26
	v_mov_b32_e32 v86, v26
	v_mov_b32_e32 v87, v26
	v_mov_b32_e32 v88, v26
	v_mov_b32_e32 v89, v26
	v_mov_b32_e32 v94, v26
	v_mov_b32_e32 v95, v26
	v_mov_b32_e32 v96, v26
	v_mov_b32_e32 v97, v26
	v_mov_b32_e32 v114, v26
	v_mov_b32_e32 v115, v26
	v_mov_b32_e32 v116, v26
	v_mov_b32_e32 v117, v26
	v_mov_b32_e32 v122, v26
	v_mov_b32_e32 v123, v26
	v_mov_b32_e32 v124, v26
	v_mov_b32_e32 v125, v26
	.p2align	6

;     __device__ __forceinline__ void a_ready(const Unit&) const { wait_cnt(w_ready, w_need); }
;     __device__ __forceinline__ void a_ready(const Unit& u) const {
;         if (ready == nullptr || u.pm != 32) return;
;         if (threadIdx.x < 64) {
;             unsigned polls = 0;
;             while ((unsigned)__builtin_amdgcn_readfirstlane(__hip_atomic_load(ready, __ATOMIC_RELAXED, __HIP_MEMORY_SCOPE_AGENT)) < need) { __builtin_amdgcn_s_sleep(2); if (++polls > (1u << 22)) break; }
;             __builtin_amdgcn_fence(__ATOMIC_ACQUIRE, "agent");
;             asm volatile("s_waitcnt vmcnt(0)" ::: "memory");
;         }
;         asm volatile("" ::: "memory"); __builtin_amdgcn_s_barrier(); asm volatile("" ::: "memory");
;     }
.LBB0_1015:
	s_or_b64 exec, exec, s[40:41]
	s_barrier
	.p2align	6

; template <class Epi, class Sched>
; __device__ __forceinline__ void gemm_phase(LAS unsigned char* lds, const Gemm g, const Sched& S, const Epi& E) {
;     ...
;         const bool has_next = S.next(ui + 1, nxt);
;         const char* nA = has_next ? (const char*)g.A + (size_t)nxt.pm * tstepA + (size_t)nxt.kt0 * kstep : cA;
;         const char* nB = has_next ? (const char*)g.Bt + (size_t)nxt.pn * tstepB + (size_t)nxt.kt0 * kstep : cB;
;         const int nt = cur.nkt;
;         if (cur.pm != 32) {
;         for (int t = 0; t < nt; t += 2) {
;             const bool last = (t == nt - 2);
;     ...
; #pragma unroll
;         for (int a = 0; a < 2; ++a)
; #pragma unroll
;             for (int b = 0; b < 2; ++b)
; #pragma unroll
;                 for (int m = 0; m < 4; ++m)
; #pragma unroll
;                     for (int n = 0; n < 2; ++n) acc[a][b][m][n] = (f32x4){0.f, 0.f, 0.f, 0.f};
.LBB0_1100:
	s_cmp_lg_u32 s18, 32
	s_cselect_b64 s[10:11], -1, 0
	s_add_i32 s20, s33, -2
	s_add_u32 s21, s14, 0x100
	s_addc_u32 s22, s15, 0
	s_add_u32 s23, s12, 0x100
	s_addc_u32 s55, s13, 0
	s_cmp_eq_u32 s18, 32
	s_mov_b64 s[16:17], -1
	s_cbranch_scc1 .LBB0_1108
	s_add_u32 s78, s12, 0x100
	s_addc_u32 s79, s13, 0
	s_add_u32 s80, s14, 0x100
	v_mov_b32_e32 v66, 0
	s_addc_u32 s81, s15, 0
	s_mov_b32 s12, 0
	v_mov_b32_e32 v67, v66
	v_mov_b32_e32 v68, v66
	s_waitcnt vmcnt(2)
	v_mov_b32_e32 v69, v66
	s_waitcnt vmcnt(0)
	v_mov_b32_e32 v70, v66
	v_mov_b32_e32 v71, v66
	v_mov_b32_e32 v72, v66
	v_mov_b32_e32 v73, v66
	v_mov_b32_e32 v74, v66
	v_mov_b32_e32 v75, v66
	v_mov_b32_e32 v76, v66
	v_mov_b32_e32 v77, v66
	v_mov_b32_e32 v78, v66
	v_mov_b32_e32 v79, v66
	v_mov_b32_e32 v80, v66
	v_mov_b32_e32 v81, v66
	v_mov_b32_e32 v86, v66
	v_mov_b32_e32 v87, v66
	v_mov_b32_e32 v88, v66
	v_mov_b32_e32 v89, v66
	v_mov_b32_e32 v94, v66
	v_mov_b32_e32 v95, v66
	v_mov_b32_e32 v96, v66
	v_mov_b32_e32 v97, v66
	v_mov_b32_e32 v102, v66
	v_mov_b32_e32 v103, v66
	v_mov_b32_e32 v104, v66
	v_mov_b32_e32 v105, v66
	v_mov_b32_e32 v110, v66
	v_mov_b32_e32 v111, v66
	v_mov_b32_e32 v112, v66
	v_mov_b32_e32 v113, v66
	v_mov_b32_e32 v82, v66
	v_mov_b32_e32 v83, v66
	v_mov_b32_e32 v84, v66
	v_mov_b32_e32 v85, v66
	v_mov_b32_e32 v90, v66
	v_mov_b32_e32 v91, v66
	v_mov_b32_e32 v92, v66
	v_mov_b32_e32 v93, v66
	v_mov_b32_e32 v98, v66
	v_mov_b32_e32 v99, v66
	v_mov_b32_e32 v100, v66
	v_mov_b32_e32 v101, v66
	v_mov_b32_e32 v106, v66
	v_mov_b32_e32 v107, v66
	v_mov_b32_e32 v108, v66
	v_mov_b32_e32 v109, v66
	v_mov_b32_e32 v114, v66
	v_mov_b32_e32 v115, v66
	v_mov_b32_e32 v116, v66
	v_mov_b32_e32 v117, v66
	v_mov_b32_e32 v118, v66
	v_mov_b32_e32 v119, v66
	v_mov_b32_e32 v120, v66
	v_mov_b32_e32 v121, v66
	v_mov_b32_e32 v122, v66
	v_mov_b32_e32 v123, v66
	v_mov_b32_e32 v124, v66
	v_mov_b32_e32 v125, v66
	v_mov_b32_e32 v126, v66
	v_mov_b32_e32 v127, v66
	v_mov_b32_e32 v128, v66
	v_mov_b32_e32 v129, v66
	v_mov_b32_e32 v2, v66
	v_mov_b32_e32 v3, v66
	v_mov_b32_e32 v4, v66
	v_mov_b32_e32 v5, v66
	v_mov_b32_e32 v6, v66
	v_mov_b32_e32 v7, v66
	v_mov_b32_e32 v8, v66
	v_mov_b32_e32 v9, v66
	v_mov_b32_e32 v10, v66
	v_mov_b32_e32 v11, v66
	v_mov_b32_e32 v12, v66
	v_mov_b32_e32 v13, v66
	v_mov_b32_e32 v14, v66
	v_mov_b32_e32 v15, v66
	v_mov_b32_e32 v16, v66
	v_mov_b32_e32 v17, v66
	v_mov_b32_e32 v18, v66
	v_mov_b32_e32 v19, v66
	v_mov_b32_e32 v20, v66
	v_mov_b32_e32 v21, v66
	v_mov_b32_e32 v22, v66
	v_mov_b32_e32 v23, v66
	v_mov_b32_e32 v24, v66
	v_mov_b32_e32 v25, v66
	v_mov_b32_e32 v34, v66
	v_mov_b32_e32 v35, v66
	v_mov_b32_e32 v36, v66
	v_mov_b32_e32 v37, v66
	v_mov_b32_e32 v38, v66
	v_mov_b32_e32 v39, v66
	v_mov_b32_e32 v40, v66
	v_mov_b32_e32 v41, v66
	v_mov_b32_e32 v26, v66
	v_mov_b32_e32 v27, v66
	v_mov_b32_e32 v28, v66
	v_mov_b32_e32 v29, v66
	v_mov_b32_e32 v30, v66
	v_mov_b32_e32 v31, v66
	v_mov_b32_e32 v32, v66
	v_mov_b32_e32 v33, v66
	v_mov_b32_e32 v42, v66
	v_mov_b32_e32 v43, v66
	v_mov_b32_e32 v44, v66
	v_mov_b32_e32 v45, v66
	v_mov_b32_e32 v46, v66
	v_mov_b32_e32 v47, v66
	v_mov_b32_e32 v48, v66
	v_mov_b32_e32 v49, v66
	v_mov_b32_e32 v50, v66
	v_mov_b32_e32 v51, v66
	v_mov_b32_e32 v52, v66
	v_mov_b32_e32 v53, v66
	v_mov_b32_e32 v54, v66
	v_mov_b32_e32 v55, v66
	v_mov_b32_e32 v56, v66
	v_mov_b32_e32 v57, v66
	v_mov_b32_e32 v58, v66
	v_mov_b32_e32 v59, v66
	v_mov_b32_e32 v60, v66
	v_mov_b32_e32 v61, v66
	v_mov_b32_e32 v62, v66
	v_mov_b32_e32 v63, v66
	v_mov_b32_e32 v64, v66
	v_mov_b32_e32 v65, v66
	.p2align	6

; template <class Epi, class Sched>
; __device__ __forceinline__ void gemm_phase(LAS unsigned char* lds, const Gemm g, const Sched& S, const Epi& E) {
;     ...
;         } else {
;         for (int t = 0; t < nt; t += 2) {
;     ...
; #pragma unroll
;         for (int a = 0; a < 2; ++a)
; #pragma unroll
;             for (int b = 0; b < 2; ++b)
; #pragma unroll
;                 for (int m = 0; m < 4; ++m)
; #pragma unroll
;                     for (int n = 0; n < 2; ++n) acc[a][b][m][n] = (f32x4){0.f, 0.f, 0.f, 0.f};
.LBB0_1108:
	s_and_b64 vcc, exec, s[16:17]
	s_cbranch_vccz .LBB0_1104
	v_mov_b32_e32 v2, 0
	s_mov_b32 s12, 0
	v_mov_b32_e32 v3, v2
	v_mov_b32_e32 v4, v2
	v_mov_b32_e32 v5, v2
	v_mov_b32_e32 v6, v2
	v_mov_b32_e32 v7, v2
	v_mov_b32_e32 v8, v2
	v_mov_b32_e32 v9, v2
	v_mov_b32_e32 v10, v2
	v_mov_b32_e32 v11, v2
	v_mov_b32_e32 v12, v2
	v_mov_b32_e32 v13, v2
	v_mov_b32_e32 v14, v2
	v_mov_b32_e32 v15, v2
	v_mov_b32_e32 v16, v2
	v_mov_b32_e32 v17, v2
	v_mov_b32_e32 v18, v2
	v_mov_b32_e32 v19, v2
	v_mov_b32_e32 v20, v2
	v_mov_b32_e32 v21, v2
	v_mov_b32_e32 v22, v2
	v_mov_b32_e32 v23, v2
	v_mov_b32_e32 v24, v2
	v_mov_b32_e32 v25, v2
	v_mov_b32_e32 v34, v2
	v_mov_b32_e32 v35, v2
	v_mov_b32_e32 v36, v2
	v_mov_b32_e32 v37, v2
	v_mov_b32_e32 v38, v2
	v_mov_b32_e32 v39, v2
	v_mov_b32_e32 v40, v2
	s_waitcnt vmcnt(1)
	v_mov_b32_e32 v41, v2
	v_mov_b32_e32 v26, v2
	v_mov_b32_e32 v27, v2
	v_mov_b32_e32 v28, v2
	v_mov_b32_e32 v29, v2
	v_mov_b32_e32 v30, v2
	v_mov_b32_e32 v31, v2
	v_mov_b32_e32 v32, v2
	v_mov_b32_e32 v33, v2
	v_mov_b32_e32 v42, v2
	v_mov_b32_e32 v43, v2
	v_mov_b32_e32 v44, v2
	v_mov_b32_e32 v45, v2
	v_mov_b32_e32 v46, v2
	v_mov_b32_e32 v47, v2
	v_mov_b32_e32 v48, v2
	v_mov_b32_e32 v49, v2
	v_mov_b32_e32 v50, v2
	v_mov_b32_e32 v51, v2
	v_mov_b32_e32 v52, v2
	v_mov_b32_e32 v53, v2
	v_mov_b32_e32 v54, v2
	v_mov_b32_e32 v55, v2
	v_mov_b32_e32 v56, v2
	v_mov_b32_e32 v57, v2
	v_mov_b32_e32 v58, v2
	v_mov_b32_e32 v59, v2
	v_mov_b32_e32 v60, v2
	v_mov_b32_e32 v61, v2
	v_mov_b32_e32 v62, v2
	v_mov_b32_e32 v63, v2
	v_mov_b32_e32 v64, v2
	v_mov_b32_e32 v65, v2
	.p2align	6
